# strategy 7.4 other half: static s_setprio 1 for waves 0-3 during the attention phase
# speedup vs baseline: 1.0071x; 1.0071x over previous
.LBB0_870:
	s_mov_b64 s[4:5], s[90:91]
	s_cmpk_gt_i32 s25, 0xff
	s_cbranch_scc1 .LBB0_953
	s_add_u32 s26, s4, 0x7a00000
	s_addc_u32 s27, s5, 0
	s_add_u32 s28, s4, 0xba00000
	s_addc_u32 s29, s5, 0
	s_add_u32 s30, s4, 0xfa00000
	s_addc_u32 s31, s5, 0
	s_add_u32 s36, s4, 0x13a00000
	s_addc_u32 s37, s5, 0
	s_lshl_b32 s38, s25, 6
	s_lshl_b32 s39, s24, 6
	v_readfirstlane_b32 s98, v214
	s_nop 3
	s_lshr_b32 s98, s98, 6
	s_cmp_ge_u32 s98, 4
	s_cbranch_scc1 .Lattn_prio_done
	s_setprio 1
